# attention loop top: first four K reads of the next body issued before the 16 p0 exps (their LDS latency hides under the exps); loop exit and prologue get their own stubs
# speedup vs baseline: 1.0047x; 1.0027x over previous
; #define SBAR() __builtin_amdgcn_sched_barrier(0)
; #define PK4(P, BASE, OUT) do { u32x4 w = {cvtpk(P[BASE + 0], P[BASE + 1]), cvtpk(P[BASE + 2], P[BASE + 3]), cvtpk(P[BASE + 4], P[BASE + 5]), cvtpk(P[BASE + 6], P[BASE + 7])}; \
;     OUT = *reinterpret_cast<bf16x8*>(&w); } while (0)
; #define PUBLISH(n) do { asm volatile("s_waitcnt vmcnt(" #n ")" ::: "memory"); asm volatile("s_waitcnt lgkmcnt(0)" ::: "memory"); __builtin_amdgcn_s_barrier(); SBAR(); } while (0)
; __device__ __forceinline__ void finishSM(f32x16& p0, f32x16& p1, float alpha, float& l_reg, bf16x8& pa0, bf16x8& pa1, bf16x8& pa2, bf16x8& pa3) {
;   for (int r = 0; r < 16; ++r) p1[r] = __builtin_amdgcn_exp2f(p1[r]);
;   float ps = 0; for (int r = 0; r < 16; ++r) ps += p0[r]; for (int r = 0; r < 16; ++r) ps += p1[r];
;   asm volatile("" : "+v"(ps));
;   l_reg = l_reg * alpha + ps;
;     ...
;   PK4(p0, 0, pa0); PK4(p0, 8, pa1); PK4(p1, 0, pa2); PK4(p1, 8, pa3);
;     ...
; }
; __device__ __forceinline__ void qkt(f32x16& p0, f32x16& p1, const bf16* Ks, const bf16x8* qr, int r32, int hi) {
;   p0 = f32x16{}; p1 = f32x16{};
;   for (int d0 = 0; d0 < 8; ++d0) { int cb = (d0 * 16 + hi * 8) * 2;
;     bf16x8 b0 = *reinterpret_cast<const bf16x8*>((const char*)Ks + KSWZ(r32, cb));
;     bf16x8 b1 = *reinterpret_cast<const bf16x8*>((const char*)Ks + KSWZ(32 + r32, cb));
;     p0 = __builtin_amdgcn_mfma_f32_32x32x16_bf16(b0, qr[d0], p0, 0, 0, 0);
;     p1 = __builtin_amdgcn_mfma_f32_32x32x16_bf16(b1, qr[d0], p1, 0, 0, 0); }
; }
; template <typename TQ> ...
;     ...
;   for (int j = 1; j + 1 < NT; j += 2) {
;     SBAR(); qkt(pB0, pB1, (const bf16*)(K_lds + (j & 3) * (int)SHM_K), qr, r32, hi);
;     finishSM(pA0, pA1, alA, l_reg, pa0, pa1, pa2, pa3); SBAR();
;     DMA_TILE(j + 2, (j + 2) & 3); SBAR();
;     pv_d0(o, vb0 + ((j - 1) & 3) * (int)SHM_V, pa0, pa1, pa2, pa3); partialSM<true>(pB0, pB1, m_reg, mnB, alB);
;     PUBLISH(4);
;     SBAR(); qkt(pA0, pA1, (const bf16*)(K_lds + ((j + 1) & 3) * (int)SHM_K), qr, r32, hi);
;     finishSM(pB0, pB1, alB, l_reg, pa0, pa1, pa2, pa3); SBAR();
;     if (j + 3 < NT) { DMA_TILE(j + 3, (j + 3) & 3); } SBAR();
;     pv_d0(o, vb0 + (j & 3) * (int)SHM_V, pa0, pa1, pa2, pa3); partialSM<true>(pA0, pA1, m_reg, mnA, alA);
.LBB0_460:
	v_add_f32_e32 v146, v146, v198
	s_add_u32 s38, s38, 0x80000
	v_add_f32_e32 v146, v146, v199
	s_addc_u32 s39, s39, 0
	s_add_i32 s73, s73, 2
	s_and_b64 vcc, exec, s[40:41]
	s_cbranch_vccnz .Lat461_exit
	s_bitcmp1_b32 s73, 1
	s_cbranch_scc1 .Lat461_b_in
.Lat461_a_in:
	s_mov_b32 s40, s33
	s_addk_i32 s33, 0xc000
	s_and_b32 s42, s33, 0xc000
	s_add_i32 s33, s57, s42
	ds_read_b128 v[80:83], v178 offset:16384
	ds_read_b128 v[84:87], v178 offset:24576
	ds_read_b128 v[198:201], v179 offset:16384
	ds_read_b128 v[202:205], v179 offset:24576
	v_exp_f32_e32 v196, v96
	v_exp_f32_e32 v197, v97
	v_exp_f32_e32 v193, v98
	v_exp_f32_e32 v195, v99
	v_exp_f32_e32 v191, v100
	v_exp_f32_e32 v194, v101
	v_exp_f32_e32 v190, v102
	v_exp_f32_e32 v192, v103
	v_exp_f32_e32 v169, v104
	v_exp_f32_e32 v171, v105
	v_exp_f32_e32 v167, v106
	v_exp_f32_e32 v170, v107
	v_exp_f32_e32 v165, v108
	v_exp_f32_e32 v168, v109
	v_exp_f32_e32 v164, v110
	v_exp_f32_e32 v166, v111
.Lat461_a_go:
	s_waitcnt lgkmcnt(3)
	v_mfma_f32_32x32x16_bf16 v[96:111], v[80:83], v[136:139], 0
	v_exp_f32_e32 v238, v64
	v_add_f32_e32 v64, v197, v196
	v_add_f32_e32 v64, v193, v64
	v_add_f32_e32 v64, v195, v64
	s_waitcnt lgkmcnt(2)
	v_mfma_f32_32x32x16_bf16 v[80:95], v[84:87], v[136:139], 0
	v_add_f32_e32 v64, v191, v64
	v_add_f32_e32 v64, v194, v64
	v_add_f32_e32 v64, v190, v64
	v_add_f32_e32 v64, v192, v64
	v_add_f32_e32 v64, v169, v64
	v_add_f32_e32 v64, v171, v64
	s_waitcnt lgkmcnt(1)
	v_mfma_f32_32x32x16_bf16 v[96:111], v[198:201], v[140:143], v[96:111]
	v_add_f32_e32 v64, v167, v64
	v_add_f32_e32 v64, v170, v64
	v_add_f32_e32 v64, v165, v64
	v_add_f32_e32 v64, v168, v64
	v_add_f32_e32 v64, v164, v64
	v_add_f32_e32 v64, v166, v64
	v_exp_f32_e32 v239, v68
	s_waitcnt lgkmcnt(0)
	v_mfma_f32_32x32x16_bf16 v[80:95], v[202:205], v[140:143], v[80:95]
	ds_read_b128 v[198:201], v180 offset:16384
	ds_read_b128 v[202:205], v180 offset:24576
	v_add_f32_e32 v64, v238, v64
	v_exp_f32_e32 v240, v69
	v_exp_f32_e32 v241, v70
	v_exp_f32_e32 v242, v71
	s_waitcnt lgkmcnt(1)
	v_mfma_f32_32x32x16_bf16 v[96:111], v[198:201], v[132:135], v[96:111]
	ds_read_b128 v[198:201], v181 offset:16384
	ds_read_b128 v[206:209], v181 offset:24576
	ds_read_b128 v[210:213], v182 offset:16384
	ds_read_b128 v[214:217], v182 offset:24576
	ds_read_b128 v[218:221], v183 offset:16384
	ds_read_b128 v[222:225], v183 offset:24576
	v_exp_f32_e32 v243, v76
	v_exp_f32_e32 v244, v77
	v_exp_f32_e32 v245, v78
	v_exp_f32_e32 v79, v79
	s_waitcnt lgkmcnt(6)
	v_mfma_f32_32x32x16_bf16 v[80:95], v[202:205], v[132:135], v[80:95]
	ds_read_b128 v[202:205], v184 offset:16384
	ds_read_b128 v[226:229], v184 offset:24576
	ds_read_b128 v[230:233], v185 offset:16384
	ds_read_b128 v[234:237], v185 offset:24576
	s_waitcnt lgkmcnt(9)
	v_mfma_f32_32x32x16_bf16 v[96:111], v[198:201], v[128:131], v[96:111]
	v_exp_f32_e32 v199, v65
	v_exp_f32_e32 v200, v66
	v_exp_f32_e32 v201, v67
	v_add_f32_e32 v64, v199, v64
	v_add_f32_e32 v64, v200, v64
	v_add_f32_e32 v64, v201, v64
	s_waitcnt lgkmcnt(8)
	v_mfma_f32_32x32x16_bf16 v[80:95], v[206:209], v[128:131], v[80:95]
	v_exp_f32_e32 v206, v72
	v_add_f32_e32 v64, v239, v64
	v_exp_f32_e32 v207, v73
	v_add_f32_e32 v64, v240, v64
	v_exp_f32_e32 v208, v74
	v_add_f32_e32 v64, v241, v64
	v_exp_f32_e32 v209, v75
	s_waitcnt lgkmcnt(7)
	v_mfma_f32_32x32x16_bf16 v[96:111], v[210:213], v[124:127], v[96:111]
	v_add_f32_e32 v64, v242, v64
	v_add_f32_e32 v64, v206, v64
	v_add_f32_e32 v64, v207, v64
	v_add_f32_e32 v64, v208, v64
	v_add_f32_e32 v64, v209, v64
	v_add_f32_e32 v64, v243, v64
	v_add_f32_e32 v64, v244, v64
	s_waitcnt lgkmcnt(6)
	v_mfma_f32_32x32x16_bf16 v[80:95], v[214:217], v[124:127], v[80:95]
	v_add_f32_e32 v64, v245, v64
	v_add_f32_e32 v198, v79, v64
	v_cvt_pk_bf16_f32 v64, v196, v197
	v_cvt_pk_bf16_f32 v65, v193, v195
	v_cvt_pk_bf16_f32 v66, v191, v194
	v_cvt_pk_bf16_f32 v67, v190, v192
	s_waitcnt lgkmcnt(5)
	v_mfma_f32_32x32x16_bf16 v[96:111], v[218:221], v[120:123], v[96:111]
	v_cvt_pk_bf16_f32 v68, v169, v171
	v_cvt_pk_bf16_f32 v69, v167, v170
	v_cvt_pk_bf16_f32 v70, v165, v168
	v_cvt_pk_bf16_f32 v71, v164, v166
	v_cvt_pk_bf16_f32 v72, v238, v199
	v_cvt_pk_bf16_f32 v73, v200, v201
	v_cvt_pk_bf16_f32 v74, v239, v240
	s_waitcnt lgkmcnt(4)
	v_mfma_f32_32x32x16_bf16 v[80:95], v[222:225], v[120:123], v[80:95]
	v_cvt_pk_bf16_f32 v75, v241, v242
	v_cvt_pk_bf16_f32 v76, v206, v207
	v_cvt_pk_bf16_f32 v77, v208, v209
	v_cvt_pk_bf16_f32 v78, v243, v244
	v_cvt_pk_bf16_f32 v79, v245, v79
	s_waitcnt lgkmcnt(3)
	v_mfma_f32_32x32x16_bf16 v[96:111], v[202:205], v[116:119], v[96:111]
	s_add_i32 s33, s40, 0x8000
	s_and_b32 s43, s33, 0xc000
	ds_read_b64_tr_b16 v[190:191], v176
	ds_read_b64_tr_b16 v[192:193], v176 offset:2048
	ds_read_b64_tr_b16 v[194:195], v176 offset:4096
	ds_read_b64_tr_b16 v[196:197], v176 offset:6144
	s_waitcnt lgkmcnt(6)
	v_mfma_f32_32x32x16_bf16 v[80:95], v[226:229], v[116:119], v[80:95]
	ds_read_b64_tr_b16 v[200:201], v176 offset:8192
	ds_read_b64_tr_b16 v[202:203], v176 offset:10240
	ds_read_b64_tr_b16 v[204:205], v176 offset:12288
	ds_read_b64_tr_b16 v[206:207], v176 offset:14336
	s_add_i32 s74, s40, 0x4000
	s_and_b32 s74, s74, 0xc000
	s_add_u32 s98, s38, s22
	s_addc_u32 s99, s39, s23
	s_add_i32 s41, s67, s74
	s_add_u32 s100, s38, s24
	s_addc_u32 s101, s39, s25
	s_mov_b32 m0, s41
	s_add_i32 s74, s72, s74
	global_load_lds_dwordx4 v156, s[98:99]
	s_waitcnt lgkmcnt(9)
; #define SBAR() __builtin_amdgcn_sched_barrier(0)
; #define PUBLISH(n) do { asm volatile("s_waitcnt vmcnt(" #n ")" ::: "memory"); asm volatile("s_waitcnt lgkmcnt(0)" ::: "memory"); __builtin_amdgcn_s_barrier(); SBAR(); } while (0)
; template <int D0> __device__ __forceinline__ void pv_one(f32x16& od, int vb, bf16x8 pa0, bf16x8 pa1, bf16x8 pa2, bf16x8 pa3) {
;   const s16x4 l0 = tr_read<v_rd_off(D0, 0, 0)>(vb), h0 = tr_read<v_rd_off(D0, 0, 1)>(vb), l1 = tr_read<v_rd_off(D0, 1, 0)>(vb), h1 = tr_read<v_rd_off(D0, 1, 1)>(vb);
;   const s16x4 l2 = tr_read<v_rd_off(D0, 2, 0)>(vb), h2 = tr_read<v_rd_off(D0, 2, 1)>(vb), l3 = tr_read<v_rd_off(D0, 3, 0)>(vb), h3 = tr_read<v_rd_off(D0, 3, 1)>(vb);
;   asm volatile("s_waitcnt lgkmcnt(0)" ::: "memory"); SBAR();
;     ...
;   od = __builtin_amdgcn_mfma_f32_32x32x16_bf16(pa0, PK(l0, h0), od, 0, 0, 0);
;   od = __builtin_amdgcn_mfma_f32_32x32x16_bf16(pa1, PK(l1, h1), od, 0, 0, 0);
;   od = __builtin_amdgcn_mfma_f32_32x32x16_bf16(pa2, PK(l2, h2), od, 0, 0, 0);
;   od = __builtin_amdgcn_mfma_f32_32x32x16_bf16(pa3, PK(l3, h3), od, 0, 0, 0);
;     ...
; }
; __device__ __forceinline__ void pv_d0(f32x16* o, int vb, bf16x8 pa0, bf16x8 pa1, bf16x8 pa2, bf16x8 pa3) {
;   pv_one<0>(o[0], vb, pa0, pa1, pa2, pa3); pv_one<1>(o[1], vb, pa0, pa1, pa2, pa3); pv_one<2>(o[2], vb, pa0, pa1, pa2, pa3); pv_one<3>(o[3], vb, pa0, pa1, pa2, pa3);
; }
; template <typename TQ> ...
;     ...
;     DMA_TILE(j + 2, (j + 2) & 3); SBAR();
;     pv_d0(o, vb0 + ((j - 1) & 3) * (int)SHM_V, pa0, pa1, pa2, pa3); partialSM<true>(pB0, pB1, m_reg, mnB, alB);
;     PUBLISH(4);
;     SBAR(); qkt(pA0, pA1, (const bf16*)(K_lds + ((j + 1) & 3) * (int)SHM_K), qr, r32, hi);
	v_mfma_f32_32x32x16_bf16 v[96:111], v[230:233], v[112:115], v[96:111]
	s_add_i32 m0, s41, 0x2000
	s_nop 0
	global_load_lds_dwordx4 v158, s[98:99]
	s_mov_b32 m0, s74
	s_nop 0
	global_load_lds_dwordx4 v162, s[100:101]
	s_waitcnt lgkmcnt(8)
	v_mfma_f32_32x32x16_bf16 v[80:95], v[234:237], v[112:115], v[80:95]
	s_add_i32 m0, s74, 0x2000
	s_nop 0
	global_load_lds_dwordx4 v160, s[100:101]
	s_nop 0
	s_waitcnt lgkmcnt(6)
	v_mfma_f32_32x32x16_bf16 v[48:63], v[64:67], v[190:193], v[48:63]
	v_exp_f32_e32 v232, v96
	ds_read_b64_tr_b16 v[190:191], v176 offset:512
	ds_read_b64_tr_b16 v[192:193], v176 offset:2560
	s_waitcnt lgkmcnt(6)
	v_mfma_f32_32x32x16_bf16 v[48:63], v[68:71], v[194:197], v[48:63]
	v_exp_f32_e32 v233, v97
	ds_read_b64_tr_b16 v[194:195], v176 offset:4608
	ds_read_b64_tr_b16 v[196:197], v176 offset:6656
	s_waitcnt lgkmcnt(6)
	v_mfma_f32_32x32x16_bf16 v[48:63], v[72:75], v[200:203], v[48:63]
	v_exp_f32_e32 v234, v98
	ds_read_b64_tr_b16 v[200:201], v176 offset:8704
	ds_read_b64_tr_b16 v[202:203], v176 offset:10752
	ds_read_b64_tr_b16 v[208:209], v176 offset:12800
	ds_read_b64_tr_b16 v[210:211], v176 offset:14848
	s_waitcnt lgkmcnt(8)
	v_mfma_f32_32x32x16_bf16 v[48:63], v[76:79], v[204:207], v[48:63]
	v_exp_f32_e32 v235, v99
	s_waitcnt lgkmcnt(6)
	v_mfma_f32_32x32x16_bf16 v[32:47], v[64:67], v[190:193], v[32:47]
	v_exp_f32_e32 v236, v100
	ds_read_b64_tr_b16 v[190:191], v176 offset:1024
	ds_read_b64_tr_b16 v[192:193], v176 offset:3072
	s_waitcnt lgkmcnt(6)
	v_mfma_f32_32x32x16_bf16 v[32:47], v[68:71], v[194:197], v[32:47]
	v_exp_f32_e32 v237, v101
	ds_read_b64_tr_b16 v[194:195], v176 offset:5120
	ds_read_b64_tr_b16 v[196:197], v176 offset:7168
	s_waitcnt lgkmcnt(6)
	v_mfma_f32_32x32x16_bf16 v[32:47], v[72:75], v[200:203], v[32:47]
	v_exp_f32_e32 v238, v102
	ds_read_b64_tr_b16 v[200:201], v176 offset:9216
	ds_read_b64_tr_b16 v[202:203], v176 offset:11264
	ds_read_b64_tr_b16 v[204:205], v176 offset:13312
	ds_read_b64_tr_b16 v[206:207], v176 offset:15360
	s_waitcnt lgkmcnt(8)
	v_mfma_f32_32x32x16_bf16 v[32:47], v[76:79], v[208:211], v[32:47]
	v_exp_f32_e32 v239, v103
	v_exp_f32_e32 v240, v104
	s_waitcnt lgkmcnt(6)
	v_mfma_f32_32x32x16_bf16 v[16:31], v[64:67], v[190:193], v[16:31]
	v_exp_f32_e32 v241, v105
	ds_read_b64_tr_b16 v[190:191], v176 offset:1536
	ds_read_b64_tr_b16 v[192:193], v176 offset:3584
	s_waitcnt lgkmcnt(6)
	v_mfma_f32_32x32x16_bf16 v[16:31], v[68:71], v[194:197], v[16:31]
	v_exp_f32_e32 v242, v106
	ds_read_b64_tr_b16 v[194:195], v176 offset:5632
	ds_read_b64_tr_b16 v[196:197], v176 offset:7680
	s_waitcnt lgkmcnt(6)
	v_mfma_f32_32x32x16_bf16 v[16:31], v[72:75], v[200:203], v[16:31]
	v_exp_f32_e32 v243, v107
	ds_read_b64_tr_b16 v[200:201], v176 offset:9728
	ds_read_b64_tr_b16 v[202:203], v176 offset:11776
	ds_read_b64_tr_b16 v[208:209], v176 offset:13824
	ds_read_b64_tr_b16 v[210:211], v176 offset:15872
	s_waitcnt lgkmcnt(8)
	v_mfma_f32_32x32x16_bf16 v[16:31], v[76:79], v[204:207], v[16:31]
	v_exp_f32_e32 v244, v108
	s_waitcnt lgkmcnt(6)
	v_mfma_f32_32x32x16_bf16 v[0:15], v[64:67], v[190:193], v[0:15]
	v_exp_f32_e32 v245, v109
	s_waitcnt lgkmcnt(4)
	v_mfma_f32_32x32x16_bf16 v[0:15], v[68:71], v[194:197], v[0:15]
	v_exp_f32_e32 v246, v110
	s_waitcnt lgkmcnt(2)
	v_mfma_f32_32x32x16_bf16 v[0:15], v[72:75], v[200:203], v[0:15]
	v_exp_f32_e32 v247, v111
	s_waitcnt vmcnt(4)
	s_waitcnt lgkmcnt(0)
	s_barrier
	v_mfma_f32_32x32x16_bf16 v[0:15], v[76:79], v[208:211], v[0:15]
	s_and_b32 s40, s40, 0xc000
	s_add_i32 s40, s57, s40
	ds_read_b128 v[64:67], v178 offset:32768
	ds_read_b128 v[68:71], v178 offset:40960
	ds_read_b128 v[190:193], v179 offset:32768
	ds_read_b128 v[194:197], v179 offset:40960
	s_waitcnt lgkmcnt(3)
	v_mfma_f32_32x32x16_bf16 v[96:111], v[64:67], v[136:139], 0
	v_exp_f32_e32 v80, v80
	v_exp_f32_e32 v81, v81
	v_exp_f32_e32 v82, v82
	v_exp_f32_e32 v83, v83
	v_exp_f32_e32 v87, v87
	v_exp_f32_e32 v248, v93
	v_exp_f32_e32 v249, v94
	s_waitcnt lgkmcnt(2)
	v_mfma_f32_32x32x16_bf16 v[64:79], v[68:71], v[136:139], 0
	s_waitcnt lgkmcnt(1)
	v_mfma_f32_32x32x16_bf16 v[96:111], v[190:193], v[140:143], v[96:111]
	s_waitcnt lgkmcnt(0)
	v_mfma_f32_32x32x16_bf16 v[64:79], v[194:197], v[140:143], v[64:79]
	ds_read_b128 v[190:193], v180 offset:32768
	ds_read_b128 v[194:197], v180 offset:40960
	s_waitcnt lgkmcnt(1)
	v_mfma_f32_32x32x16_bf16 v[96:111], v[190:193], v[132:135], v[96:111]
	ds_read_b128 v[190:193], v181 offset:32768
	ds_read_b128 v[200:203], v181 offset:40960
	ds_read_b128 v[204:207], v182 offset:32768
	ds_read_b128 v[208:211], v182 offset:40960
	ds_read_b128 v[212:215], v183 offset:32768
	ds_read_b128 v[216:219], v183 offset:40960
	s_waitcnt lgkmcnt(6)
	v_mfma_f32_32x32x16_bf16 v[64:79], v[194:197], v[132:135], v[64:79]
	ds_read_b128 v[194:197], v184 offset:32768
	ds_read_b128 v[220:223], v184 offset:40960
	ds_read_b128 v[224:227], v185 offset:32768
	ds_read_b128 v[228:231], v185 offset:40960
	s_waitcnt lgkmcnt(9)
	v_mfma_f32_32x32x16_bf16 v[96:111], v[190:193], v[128:131], v[96:111]
	s_cmp_ge_u32 s73, s37
	s_cselect_b64 s[40:41], -1, 0
	s_and_b64 vcc, exec, s[40:41]
	s_cbranch_vccnz .LBB0_463
	s_add_i32 s74, s67, s43
	s_add_u32 s98, s38, s26
	s_addc_u32 s99, s39, s27
	s_mov_b32 m0, s74
	s_add_i32 s43, s72, s43
	global_load_lds_dwordx4 v156, s[98:99]
	s_add_u32 s100, s38, s28
	s_addc_u32 s101, s39, s29
	s_add_i32 m0, s74, 0x2000
	s_nop 0
	global_load_lds_dwordx4 v158, s[98:99]
	s_mov_b32 m0, s43
	s_nop 0
	global_load_lds_dwordx4 v162, s[100:101]
	s_add_i32 m0, s43, 0x2000
	s_nop 0
	global_load_lds_dwordx4 v160, s[100:101]

; #define SBAR() __builtin_amdgcn_sched_barrier(0)
; #define PK4(P, BASE, OUT) do { u32x4 w = {cvtpk(P[BASE + 0], P[BASE + 1]), cvtpk(P[BASE + 2], P[BASE + 3]), cvtpk(P[BASE + 4], P[BASE + 5]), cvtpk(P[BASE + 6], P[BASE + 7])}; \
;     OUT = *reinterpret_cast<bf16x8*>(&w); } while (0)
; __device__ __forceinline__ void finishSM(f32x16& p0, f32x16& p1, float alpha, float& l_reg, bf16x8& pa0, bf16x8& pa1, bf16x8& pa2, bf16x8& pa3) {
;   for (int r = 0; r < 16; ++r) p1[r] = __builtin_amdgcn_exp2f(p1[r]);
;   float ps = 0; for (int r = 0; r < 16; ++r) ps += p0[r]; for (int r = 0; r < 16; ++r) ps += p1[r];
;   asm volatile("" : "+v"(ps));
;   l_reg = l_reg * alpha + ps;
;     ...
;   PK4(p0, 0, pa0); PK4(p0, 8, pa1); PK4(p1, 0, pa2); PK4(p1, 8, pa3);
;     ...
; }
; __device__ __forceinline__ void qkt(f32x16& p0, f32x16& p1, const bf16* Ks, const bf16x8* qr, int r32, int hi) {
;   p0 = f32x16{}; p1 = f32x16{};
;   for (int d0 = 0; d0 < 8; ++d0) { int cb = (d0 * 16 + hi * 8) * 2;
;     bf16x8 b0 = *reinterpret_cast<const bf16x8*>((const char*)Ks + KSWZ(r32, cb));
;     bf16x8 b1 = *reinterpret_cast<const bf16x8*>((const char*)Ks + KSWZ(32 + r32, cb));
;     p0 = __builtin_amdgcn_mfma_f32_32x32x16_bf16(b0, qr[d0], p0, 0, 0, 0);
;     p1 = __builtin_amdgcn_mfma_f32_32x32x16_bf16(b1, qr[d0], p1, 0, 0, 0); }
; }
; template <typename TQ> ...
;     ...
;     SBAR(); qkt(pA0, pA1, (const bf16*)(K_lds + ((j + 1) & 3) * (int)SHM_K), qr, r32, hi);
;     finishSM(pB0, pB1, alB, l_reg, pa0, pa1, pa2, pa3); SBAR();
;     if (j + 3 < NT) { DMA_TILE(j + 3, (j + 3) & 3); } SBAR();
;     pv_d0(o, vb0 + (j & 3) * (int)SHM_V, pa0, pa1, pa2, pa3); partialSM<true>(pA0, pA1, m_reg, mnA, alA);
.Lat461_b:
.Lat461_b_in:
	s_mov_b32 s40, s33
	s_addk_i32 s33, 0xc000
	s_and_b32 s42, s33, 0xc000
	s_add_i32 s33, s57, s42
	ds_read_b128 v[80:83], v178 offset:49152
	ds_read_b128 v[84:87], v178 offset:57344
	ds_read_b128 v[198:201], v179 offset:49152
	ds_read_b128 v[202:205], v179 offset:57344
	v_exp_f32_e32 v196, v96
	v_exp_f32_e32 v197, v97
	v_exp_f32_e32 v193, v98
	v_exp_f32_e32 v195, v99
	v_exp_f32_e32 v191, v100
	v_exp_f32_e32 v194, v101
	v_exp_f32_e32 v190, v102
	v_exp_f32_e32 v192, v103
	v_exp_f32_e32 v169, v104
	v_exp_f32_e32 v171, v105
	v_exp_f32_e32 v167, v106
	v_exp_f32_e32 v170, v107
	v_exp_f32_e32 v165, v108
	v_exp_f32_e32 v168, v109
	v_exp_f32_e32 v164, v110
	v_exp_f32_e32 v166, v111
	s_waitcnt lgkmcnt(3)
	v_mfma_f32_32x32x16_bf16 v[96:111], v[80:83], v[136:139], 0
	v_exp_f32_e32 v238, v64
	v_add_f32_e32 v64, v197, v196
	v_add_f32_e32 v64, v193, v64
	v_add_f32_e32 v64, v195, v64
	s_waitcnt lgkmcnt(2)
	v_mfma_f32_32x32x16_bf16 v[80:95], v[84:87], v[136:139], 0
	v_add_f32_e32 v64, v191, v64
	v_add_f32_e32 v64, v194, v64
	v_add_f32_e32 v64, v190, v64
	v_add_f32_e32 v64, v192, v64
	v_add_f32_e32 v64, v169, v64
	v_add_f32_e32 v64, v171, v64
	s_waitcnt lgkmcnt(1)
	v_mfma_f32_32x32x16_bf16 v[96:111], v[198:201], v[140:143], v[96:111]
	v_add_f32_e32 v64, v167, v64
	v_add_f32_e32 v64, v170, v64
	v_add_f32_e32 v64, v165, v64
	v_add_f32_e32 v64, v168, v64
	v_add_f32_e32 v64, v164, v64
	v_add_f32_e32 v64, v166, v64
	v_exp_f32_e32 v239, v68
	s_waitcnt lgkmcnt(0)
	v_mfma_f32_32x32x16_bf16 v[80:95], v[202:205], v[140:143], v[80:95]
	ds_read_b128 v[198:201], v180 offset:49152
	ds_read_b128 v[202:205], v180 offset:57344
	v_add_f32_e32 v64, v238, v64
	v_exp_f32_e32 v240, v69
	v_exp_f32_e32 v241, v70
	v_exp_f32_e32 v242, v71
	s_waitcnt lgkmcnt(1)
	v_mfma_f32_32x32x16_bf16 v[96:111], v[198:201], v[132:135], v[96:111]
	ds_read_b128 v[198:201], v181 offset:49152
	ds_read_b128 v[206:209], v181 offset:57344
	ds_read_b128 v[210:213], v182 offset:49152
	ds_read_b128 v[214:217], v182 offset:57344
	ds_read_b128 v[218:221], v183 offset:49152
	ds_read_b128 v[222:225], v183 offset:57344
	v_exp_f32_e32 v243, v76
	v_exp_f32_e32 v244, v77
	v_exp_f32_e32 v245, v78
	v_exp_f32_e32 v79, v79
	s_waitcnt lgkmcnt(6)
	v_mfma_f32_32x32x16_bf16 v[80:95], v[202:205], v[132:135], v[80:95]
	ds_read_b128 v[202:205], v184 offset:49152
	ds_read_b128 v[226:229], v184 offset:57344
	ds_read_b128 v[230:233], v185 offset:49152
	ds_read_b128 v[234:237], v185 offset:57344
	s_waitcnt lgkmcnt(9)
	v_mfma_f32_32x32x16_bf16 v[96:111], v[198:201], v[128:131], v[96:111]
	v_exp_f32_e32 v199, v65
	v_exp_f32_e32 v200, v66
	v_exp_f32_e32 v201, v67
	v_add_f32_e32 v64, v199, v64
	v_add_f32_e32 v64, v200, v64
	v_add_f32_e32 v64, v201, v64
	s_waitcnt lgkmcnt(8)
	v_mfma_f32_32x32x16_bf16 v[80:95], v[206:209], v[128:131], v[80:95]
	v_exp_f32_e32 v206, v72
	v_add_f32_e32 v64, v239, v64
	v_exp_f32_e32 v207, v73
	v_add_f32_e32 v64, v240, v64
	v_exp_f32_e32 v208, v74
	v_add_f32_e32 v64, v241, v64
	v_exp_f32_e32 v209, v75
	s_waitcnt lgkmcnt(7)
	v_mfma_f32_32x32x16_bf16 v[96:111], v[210:213], v[124:127], v[96:111]
	v_add_f32_e32 v64, v242, v64
	v_add_f32_e32 v64, v206, v64
	v_add_f32_e32 v64, v207, v64
	v_add_f32_e32 v64, v208, v64
	v_add_f32_e32 v64, v209, v64
	v_add_f32_e32 v64, v243, v64
	v_add_f32_e32 v64, v244, v64
	s_waitcnt lgkmcnt(6)
	v_mfma_f32_32x32x16_bf16 v[80:95], v[214:217], v[124:127], v[80:95]
	v_add_f32_e32 v64, v245, v64
	v_add_f32_e32 v198, v79, v64
	v_cvt_pk_bf16_f32 v64, v196, v197
	v_cvt_pk_bf16_f32 v65, v193, v195
	v_cvt_pk_bf16_f32 v66, v191, v194
	v_cvt_pk_bf16_f32 v67, v190, v192
	s_waitcnt lgkmcnt(5)
	v_mfma_f32_32x32x16_bf16 v[96:111], v[218:221], v[120:123], v[96:111]
	v_cvt_pk_bf16_f32 v68, v169, v171
	v_cvt_pk_bf16_f32 v69, v167, v170
	v_cvt_pk_bf16_f32 v70, v165, v168
	v_cvt_pk_bf16_f32 v71, v164, v166
	v_cvt_pk_bf16_f32 v72, v238, v199
	v_cvt_pk_bf16_f32 v73, v200, v201
	v_cvt_pk_bf16_f32 v74, v239, v240
	s_waitcnt lgkmcnt(4)
	v_mfma_f32_32x32x16_bf16 v[80:95], v[222:225], v[120:123], v[80:95]
	v_cvt_pk_bf16_f32 v75, v241, v242
	v_cvt_pk_bf16_f32 v76, v206, v207
	v_cvt_pk_bf16_f32 v77, v208, v209
	v_cvt_pk_bf16_f32 v78, v243, v244
	v_cvt_pk_bf16_f32 v79, v245, v79
	s_waitcnt lgkmcnt(3)
	v_mfma_f32_32x32x16_bf16 v[96:111], v[202:205], v[116:119], v[96:111]
	s_add_i32 s33, s40, 0x8000
	s_and_b32 s43, s33, 0xc000
	ds_read_b64_tr_b16 v[190:191], v176 offset:32768
	ds_read_b64_tr_b16 v[192:193], v176 offset:34816
	ds_read_b64_tr_b16 v[194:195], v176 offset:36864
	ds_read_b64_tr_b16 v[196:197], v176 offset:38912
	s_waitcnt lgkmcnt(6)
	v_mfma_f32_32x32x16_bf16 v[80:95], v[226:229], v[116:119], v[80:95]
	ds_read_b64_tr_b16 v[200:201], v176 offset:40960
	ds_read_b64_tr_b16 v[202:203], v176 offset:43008
	ds_read_b64_tr_b16 v[204:205], v176 offset:45056
	ds_read_b64_tr_b16 v[206:207], v176 offset:47104
	s_add_i32 s74, s40, 0x4000
	s_and_b32 s74, s74, 0xc000
	s_add_u32 s98, s38, s22
	s_addc_u32 s99, s39, s23
	s_add_i32 s41, s67, s74
	s_add_u32 s100, s38, s24
	s_addc_u32 s101, s39, s25
	s_mov_b32 m0, s41
	s_add_i32 s74, s72, s74
	global_load_lds_dwordx4 v156, s[98:99]
	s_waitcnt lgkmcnt(9)
; #define SBAR() __builtin_amdgcn_sched_barrier(0)
; #define PUBLISH(n) do { asm volatile("s_waitcnt vmcnt(" #n ")" ::: "memory"); asm volatile("s_waitcnt lgkmcnt(0)" ::: "memory"); __builtin_amdgcn_s_barrier(); SBAR(); } while (0)
; template <int D0> __device__ __forceinline__ void pv_one(f32x16& od, int vb, bf16x8 pa0, bf16x8 pa1, bf16x8 pa2, bf16x8 pa3) {
;   const s16x4 l0 = tr_read<v_rd_off(D0, 0, 0)>(vb), h0 = tr_read<v_rd_off(D0, 0, 1)>(vb), l1 = tr_read<v_rd_off(D0, 1, 0)>(vb), h1 = tr_read<v_rd_off(D0, 1, 1)>(vb);
;   const s16x4 l2 = tr_read<v_rd_off(D0, 2, 0)>(vb), h2 = tr_read<v_rd_off(D0, 2, 1)>(vb), l3 = tr_read<v_rd_off(D0, 3, 0)>(vb), h3 = tr_read<v_rd_off(D0, 3, 1)>(vb);
;   asm volatile("s_waitcnt lgkmcnt(0)" ::: "memory"); SBAR();
;     ...
;   od = __builtin_amdgcn_mfma_f32_32x32x16_bf16(pa0, PK(l0, h0), od, 0, 0, 0);
;   od = __builtin_amdgcn_mfma_f32_32x32x16_bf16(pa1, PK(l1, h1), od, 0, 0, 0);
;   od = __builtin_amdgcn_mfma_f32_32x32x16_bf16(pa2, PK(l2, h2), od, 0, 0, 0);
;   od = __builtin_amdgcn_mfma_f32_32x32x16_bf16(pa3, PK(l3, h3), od, 0, 0, 0);
;     ...
; }
; __device__ __forceinline__ void pv_d0(f32x16* o, int vb, bf16x8 pa0, bf16x8 pa1, bf16x8 pa2, bf16x8 pa3) {
;   pv_one<0>(o[0], vb, pa0, pa1, pa2, pa3); pv_one<1>(o[1], vb, pa0, pa1, pa2, pa3); pv_one<2>(o[2], vb, pa0, pa1, pa2, pa3); pv_one<3>(o[3], vb, pa0, pa1, pa2, pa3);
; }
; template <typename TQ> ...
;     ...
;   for (int j = 1; j + 1 < NT; j += 2) {
;     SBAR(); qkt(pB0, pB1, (const bf16*)(K_lds + (j & 3) * (int)SHM_K), qr, r32, hi);
;     finishSM(pA0, pA1, alA, l_reg, pa0, pa1, pa2, pa3); SBAR();
;     DMA_TILE(j + 2, (j + 2) & 3); SBAR();
;     pv_d0(o, vb0 + ((j - 1) & 3) * (int)SHM_V, pa0, pa1, pa2, pa3); partialSM<true>(pB0, pB1, m_reg, mnB, alB);
;     PUBLISH(4);
;     SBAR(); qkt(pA0, pA1, (const bf16*)(K_lds + ((j + 1) & 3) * (int)SHM_K), qr, r32, hi);
;     finishSM(pB0, pB1, alB, l_reg, pa0, pa1, pa2, pa3); SBAR();
;     if (j + 3 < NT) { DMA_TILE(j + 3, (j + 3) & 3); } SBAR();
;     pv_d0(o, vb0 + (j & 3) * (int)SHM_V, pa0, pa1, pa2, pa3); partialSM<true>(pA0, pA1, m_reg, mnA, alA);
;     if (j + 3 < NT) { PUBLISH(4); } else { PUBLISH(0); }
;   }
	v_mfma_f32_32x32x16_bf16 v[96:111], v[230:233], v[112:115], v[96:111]
	s_add_i32 m0, s41, 0x2000
	s_nop 0
	global_load_lds_dwordx4 v158, s[98:99]
	s_mov_b32 m0, s74
	s_nop 0
	global_load_lds_dwordx4 v162, s[100:101]
	s_waitcnt lgkmcnt(8)
	v_mfma_f32_32x32x16_bf16 v[80:95], v[234:237], v[112:115], v[80:95]
	s_add_i32 m0, s74, 0x2000
	s_nop 0
	global_load_lds_dwordx4 v160, s[100:101]
	s_nop 0
	s_waitcnt lgkmcnt(6)
	v_mfma_f32_32x32x16_bf16 v[48:63], v[64:67], v[190:193], v[48:63]
	v_exp_f32_e32 v232, v96
	ds_read_b64_tr_b16 v[190:191], v176 offset:33280
	ds_read_b64_tr_b16 v[192:193], v176 offset:35328
	s_waitcnt lgkmcnt(6)
	v_mfma_f32_32x32x16_bf16 v[48:63], v[68:71], v[194:197], v[48:63]
	v_exp_f32_e32 v233, v97
	ds_read_b64_tr_b16 v[194:195], v176 offset:37376
	ds_read_b64_tr_b16 v[196:197], v176 offset:39424
	s_waitcnt lgkmcnt(6)
	v_mfma_f32_32x32x16_bf16 v[48:63], v[72:75], v[200:203], v[48:63]
	v_exp_f32_e32 v234, v98
	ds_read_b64_tr_b16 v[200:201], v176 offset:41472
	ds_read_b64_tr_b16 v[202:203], v176 offset:43520
	ds_read_b64_tr_b16 v[208:209], v176 offset:45568
	ds_read_b64_tr_b16 v[210:211], v176 offset:47616
	s_waitcnt lgkmcnt(8)
	v_mfma_f32_32x32x16_bf16 v[48:63], v[76:79], v[204:207], v[48:63]
	v_exp_f32_e32 v235, v99
	s_waitcnt lgkmcnt(6)
	v_mfma_f32_32x32x16_bf16 v[32:47], v[64:67], v[190:193], v[32:47]
	v_exp_f32_e32 v236, v100
	ds_read_b64_tr_b16 v[190:191], v176 offset:33792
	ds_read_b64_tr_b16 v[192:193], v176 offset:35840
	s_waitcnt lgkmcnt(6)
	v_mfma_f32_32x32x16_bf16 v[32:47], v[68:71], v[194:197], v[32:47]
	v_exp_f32_e32 v237, v101
	ds_read_b64_tr_b16 v[194:195], v176 offset:37888
	ds_read_b64_tr_b16 v[196:197], v176 offset:39936
	s_waitcnt lgkmcnt(6)
	v_mfma_f32_32x32x16_bf16 v[32:47], v[72:75], v[200:203], v[32:47]
	v_exp_f32_e32 v238, v102
	ds_read_b64_tr_b16 v[200:201], v176 offset:41984
	ds_read_b64_tr_b16 v[202:203], v176 offset:44032
	ds_read_b64_tr_b16 v[204:205], v176 offset:46080
	ds_read_b64_tr_b16 v[206:207], v176 offset:48128
	s_waitcnt lgkmcnt(8)
	v_mfma_f32_32x32x16_bf16 v[32:47], v[76:79], v[208:211], v[32:47]
	v_exp_f32_e32 v239, v103
	v_exp_f32_e32 v240, v104
	s_waitcnt lgkmcnt(6)
	v_mfma_f32_32x32x16_bf16 v[16:31], v[64:67], v[190:193], v[16:31]
	v_exp_f32_e32 v241, v105
	ds_read_b64_tr_b16 v[190:191], v176 offset:34304
	ds_read_b64_tr_b16 v[192:193], v176 offset:36352
	s_waitcnt lgkmcnt(6)
	v_mfma_f32_32x32x16_bf16 v[16:31], v[68:71], v[194:197], v[16:31]
	v_exp_f32_e32 v242, v106
	ds_read_b64_tr_b16 v[194:195], v176 offset:38400
	ds_read_b64_tr_b16 v[196:197], v176 offset:40448
	s_waitcnt lgkmcnt(6)
	v_mfma_f32_32x32x16_bf16 v[16:31], v[72:75], v[200:203], v[16:31]
	v_exp_f32_e32 v243, v107
	ds_read_b64_tr_b16 v[200:201], v176 offset:42496
	ds_read_b64_tr_b16 v[202:203], v176 offset:44544
	ds_read_b64_tr_b16 v[208:209], v176 offset:46592
	ds_read_b64_tr_b16 v[210:211], v176 offset:48640
	s_waitcnt lgkmcnt(8)
	v_mfma_f32_32x32x16_bf16 v[16:31], v[76:79], v[204:207], v[16:31]
	v_exp_f32_e32 v244, v108
	s_waitcnt lgkmcnt(6)
	v_mfma_f32_32x32x16_bf16 v[0:15], v[64:67], v[190:193], v[0:15]
	v_exp_f32_e32 v245, v109
	s_waitcnt lgkmcnt(4)
	v_mfma_f32_32x32x16_bf16 v[0:15], v[68:71], v[194:197], v[0:15]
	v_exp_f32_e32 v246, v110
	s_waitcnt lgkmcnt(2)
	v_mfma_f32_32x32x16_bf16 v[0:15], v[72:75], v[200:203], v[0:15]
	v_exp_f32_e32 v247, v111
	s_waitcnt vmcnt(4)
	s_waitcnt lgkmcnt(0)
	s_barrier
	v_mfma_f32_32x32x16_bf16 v[0:15], v[76:79], v[208:211], v[0:15]
	s_and_b32 s40, s40, 0xc000
	s_add_i32 s40, s57, s40
	ds_read_b128 v[64:67], v178
	ds_read_b128 v[68:71], v178 offset:8192
	ds_read_b128 v[190:193], v179
	ds_read_b128 v[194:197], v179 offset:8192
	s_waitcnt lgkmcnt(3)
	v_mfma_f32_32x32x16_bf16 v[96:111], v[64:67], v[136:139], 0
	v_exp_f32_e32 v80, v80
	v_exp_f32_e32 v81, v81
	v_exp_f32_e32 v82, v82
	v_exp_f32_e32 v83, v83
	v_exp_f32_e32 v87, v87
	v_exp_f32_e32 v248, v93
	v_exp_f32_e32 v249, v94
	s_waitcnt lgkmcnt(2)
	v_mfma_f32_32x32x16_bf16 v[64:79], v[68:71], v[136:139], 0
	s_waitcnt lgkmcnt(1)
	v_mfma_f32_32x32x16_bf16 v[96:111], v[190:193], v[140:143], v[96:111]
	s_waitcnt lgkmcnt(0)
	v_mfma_f32_32x32x16_bf16 v[64:79], v[194:197], v[140:143], v[64:79]
	ds_read_b128 v[190:193], v180
	ds_read_b128 v[194:197], v180 offset:8192
	s_waitcnt lgkmcnt(1)
	v_mfma_f32_32x32x16_bf16 v[96:111], v[190:193], v[132:135], v[96:111]
	ds_read_b128 v[190:193], v181
	ds_read_b128 v[200:203], v181 offset:8192
	ds_read_b128 v[204:207], v182
	ds_read_b128 v[208:211], v182 offset:8192
	ds_read_b128 v[212:215], v183
	ds_read_b128 v[216:219], v183 offset:8192
	s_waitcnt lgkmcnt(6)
	v_mfma_f32_32x32x16_bf16 v[64:79], v[194:197], v[132:135], v[64:79]
	ds_read_b128 v[194:197], v184
	ds_read_b128 v[220:223], v184 offset:8192
	ds_read_b128 v[224:227], v185
	ds_read_b128 v[228:231], v185 offset:8192
	s_waitcnt lgkmcnt(9)
	v_mfma_f32_32x32x16_bf16 v[96:111], v[190:193], v[128:131], v[96:111]
	s_cmp_ge_u32 s73, s37
	s_cselect_b64 s[40:41], -1, 0
	s_and_b64 vcc, exec, s[40:41]
	s_cbranch_vccnz .Lat463_b

; #define SBAR() __builtin_amdgcn_sched_barrier(0)
; template <typename TQ> ...
;     ...
;     if (j + 3 < NT) { DMA_TILE(j + 3, (j + 3) & 3); } SBAR();
	s_add_i32 s74, s67, s43
	s_add_u32 s98, s38, s26
	s_addc_u32 s99, s39, s27
	s_mov_b32 m0, s74
	s_add_i32 s43, s72, s43
	global_load_lds_dwordx4 v156, s[98:99]
	s_add_u32 s100, s38, s28
	s_addc_u32 s101, s39, s29
	s_add_i32 m0, s74, 0x2000
	s_nop 0
	global_load_lds_dwordx4 v158, s[98:99]
	s_mov_b32 m0, s43
	s_nop 0
	global_load_lds_dwordx4 v162, s[100:101]
	s_add_i32 m0, s43, 0x2000
	s_nop 0
	global_load_lds_dwordx4 v160, s[100:101]

; #define SBAR() __builtin_amdgcn_sched_barrier(0)
; #define PUBLISH(n) do { asm volatile("s_waitcnt vmcnt(" #n ")" ::: "memory"); asm volatile("s_waitcnt lgkmcnt(0)" ::: "memory"); __builtin_amdgcn_s_barrier(); SBAR(); } while (0)
; template <typename TQ> ...
;     ...
;   for (int j = 1; j + 1 < NT; j += 2) {
;     SBAR(); qkt(pB0, pB1, (const bf16*)(K_lds + (j & 3) * (int)SHM_K), qr, r32, hi);
;     finishSM(pA0, pA1, alA, l_reg, pa0, pa1, pa2, pa3); SBAR();
;     DMA_TILE(j + 2, (j + 2) & 3); SBAR();
;     pv_d0(o, vb0 + ((j - 1) & 3) * (int)SHM_V, pa0, pa1, pa2, pa3); partialSM<true>(pB0, pB1, m_reg, mnB, alB);
;     PUBLISH(4);
;     SBAR(); qkt(pA0, pA1, (const bf16*)(K_lds + ((j + 1) & 3) * (int)SHM_K), qr, r32, hi);
;     finishSM(pB0, pB1, alB, l_reg, pa0, pa1, pa2, pa3); SBAR();
;     if (j + 3 < NT) { DMA_TILE(j + 3, (j + 3) & 3); } SBAR();
;     pv_d0(o, vb0 + (j & 3) * (int)SHM_V, pa0, pa1, pa2, pa3); partialSM<true>(pA0, pA1, m_reg, mnA, alA);
;     if (j + 3 < NT) { PUBLISH(4); } else { PUBLISH(0); }
;   }
;   SBAR(); qkt(pB0, pB1, (const bf16*)(K_lds + ((NT - 1) & 3) * (int)SHM_K), qr, r32, hi);
;   finishSM(pA0, pA1, alA, l_reg, pa0, pa1, pa2, pa3); SBAR();
;   pv_d0(o, vb0 + ((NT - 2) & 3) * (int)SHM_V, pa0, pa1, pa2, pa3); partialSM<true>(pB0, pB1, m_reg, mnB, alB);
.Lat461_exit:
	v_exp_f32_e32 v196, v96
	v_exp_f32_e32 v197, v97
	v_exp_f32_e32 v193, v98
	v_exp_f32_e32 v195, v99
	v_exp_f32_e32 v191, v100
	v_exp_f32_e32 v194, v101
	v_exp_f32_e32 v190, v102
	v_exp_f32_e32 v192, v103
	v_exp_f32_e32 v169, v104
	v_exp_f32_e32 v171, v105
	v_exp_f32_e32 v167, v106
	v_exp_f32_e32 v170, v107
	v_exp_f32_e32 v165, v108
	v_exp_f32_e32 v168, v109
	v_exp_f32_e32 v164, v110
	v_exp_f32_e32 v166, v111
	s_branch .LBB0_467
.LBB0_461:
	s_mov_b32 s40, s33
	s_addk_i32 s33, 0xc000
	s_and_b32 s42, s33, 0xc000
	s_add_i32 s33, s57, s42
	ds_read_b128 v[80:83], v178 offset:16384
	ds_read_b128 v[84:87], v178 offset:24576
	ds_read_b128 v[198:201], v179 offset:16384
	ds_read_b128 v[202:205], v179 offset:24576
	s_branch .Lat461_a_go

; #define SBAR() __builtin_amdgcn_sched_barrier(0)
; #define PK4(P, BASE, OUT) do { u32x4 w = {cvtpk(P[BASE + 0], P[BASE + 1]), cvtpk(P[BASE + 2], P[BASE + 3]), cvtpk(P[BASE + 4], P[BASE + 5]), cvtpk(P[BASE + 6], P[BASE + 7])}; \
;     OUT = *reinterpret_cast<bf16x8*>(&w); } while (0)
; #define PUBLISH(n) do { asm volatile("s_waitcnt vmcnt(" #n ")" ::: "memory"); asm volatile("s_waitcnt lgkmcnt(0)" ::: "memory"); __builtin_amdgcn_s_barrier(); SBAR(); } while (0)
; __device__ __forceinline__ void finishSM(f32x16& p0, f32x16& p1, float alpha, float& l_reg, bf16x8& pa0, bf16x8& pa1, bf16x8& pa2, bf16x8& pa3) {
;   for (int r = 0; r < 16; ++r) p1[r] = __builtin_amdgcn_exp2f(p1[r]);
;   float ps = 0; for (int r = 0; r < 16; ++r) ps += p0[r]; for (int r = 0; r < 16; ++r) ps += p1[r];
;   asm volatile("" : "+v"(ps));
;   l_reg = l_reg * alpha + ps;
;     ...
;   PK4(p0, 0, pa0); PK4(p0, 8, pa1); PK4(p1, 0, pa2); PK4(p1, 8, pa3);
;     ...
; }
; __device__ __forceinline__ void qkt(f32x16& p0, f32x16& p1, const bf16* Ks, const bf16x8* qr, int r32, int hi) {
;   p0 = f32x16{}; p1 = f32x16{};
;   for (int d0 = 0; d0 < 8; ++d0) { int cb = (d0 * 16 + hi * 8) * 2;
;     bf16x8 b0 = *reinterpret_cast<const bf16x8*>((const char*)Ks + KSWZ(r32, cb));
;     bf16x8 b1 = *reinterpret_cast<const bf16x8*>((const char*)Ks + KSWZ(32 + r32, cb));
;     p0 = __builtin_amdgcn_mfma_f32_32x32x16_bf16(b0, qr[d0], p0, 0, 0, 0);
;     p1 = __builtin_amdgcn_mfma_f32_32x32x16_bf16(b1, qr[d0], p1, 0, 0, 0); }
; }
; template <typename TQ> ...
;     ...
;   for (int j = 1; j + 1 < NT; j += 2) {
;     SBAR(); qkt(pB0, pB1, (const bf16*)(K_lds + (j & 3) * (int)SHM_K), qr, r32, hi);
;     finishSM(pA0, pA1, alA, l_reg, pa0, pa1, pa2, pa3); SBAR();
;     DMA_TILE(j + 2, (j + 2) & 3); SBAR();
;     pv_d0(o, vb0 + ((j - 1) & 3) * (int)SHM_V, pa0, pa1, pa2, pa3); partialSM<true>(pB0, pB1, m_reg, mnB, alB);
;     PUBLISH(4);
;     SBAR(); qkt(pA0, pA1, (const bf16*)(K_lds + ((j + 1) & 3) * (int)SHM_K), qr, r32, hi);
;     finishSM(pB0, pB1, alB, l_reg, pa0, pa1, pa2, pa3); SBAR();
;     if (j + 3 < NT) { DMA_TILE(j + 3, (j + 3) & 3); } SBAR();
;     pv_d0(o, vb0 + (j & 3) * (int)SHM_V, pa0, pa1, pa2, pa3); partialSM<true>(pA0, pA1, m_reg, mnA, alA);
.LBB0_1364:
	v_add_f32_e32 v146, v146, v198
	s_add_u32 s38, s38, 0x80000
	v_add_f32_e32 v146, v146, v199
	s_addc_u32 s39, s39, 0
	s_add_i32 s72, s72, 2
	s_and_b64 vcc, exec, s[40:41]
	s_cbranch_vccnz .Lat1365_exit
	s_bitcmp1_b32 s72, 1
	s_cbranch_scc1 .Lat1365_b_in
.Lat1365_a_in:
	s_mov_b32 s40, s33
	s_addk_i32 s33, 0xc000
	s_and_b32 s42, s33, 0xc000
	s_add_i32 s33, s56, s42
	ds_read_b128 v[80:83], v178 offset:16384
	ds_read_b128 v[84:87], v178 offset:24576
	ds_read_b128 v[198:201], v179 offset:16384
	ds_read_b128 v[202:205], v179 offset:24576
	v_exp_f32_e32 v196, v96
	v_exp_f32_e32 v197, v97
	v_exp_f32_e32 v193, v98
	v_exp_f32_e32 v195, v99
	v_exp_f32_e32 v191, v100
	v_exp_f32_e32 v194, v101
	v_exp_f32_e32 v190, v102
	v_exp_f32_e32 v192, v103
	v_exp_f32_e32 v169, v104
	v_exp_f32_e32 v171, v105
	v_exp_f32_e32 v167, v106
	v_exp_f32_e32 v170, v107
	v_exp_f32_e32 v165, v108
	v_exp_f32_e32 v168, v109
	v_exp_f32_e32 v164, v110
	v_exp_f32_e32 v166, v111
.Lat1365_a_go:
	s_waitcnt lgkmcnt(3)
	v_mfma_f32_32x32x16_bf16 v[96:111], v[80:83], v[136:139], 0
	v_exp_f32_e32 v238, v64
	v_add_f32_e32 v64, v197, v196
	v_add_f32_e32 v64, v193, v64
	v_add_f32_e32 v64, v195, v64
	s_waitcnt lgkmcnt(2)
	v_mfma_f32_32x32x16_bf16 v[80:95], v[84:87], v[136:139], 0
	v_add_f32_e32 v64, v191, v64
	v_add_f32_e32 v64, v194, v64
	v_add_f32_e32 v64, v190, v64
	v_add_f32_e32 v64, v192, v64
	v_add_f32_e32 v64, v169, v64
	v_add_f32_e32 v64, v171, v64
	s_waitcnt lgkmcnt(1)
	v_mfma_f32_32x32x16_bf16 v[96:111], v[198:201], v[140:143], v[96:111]
	v_add_f32_e32 v64, v167, v64
	v_add_f32_e32 v64, v170, v64
	v_add_f32_e32 v64, v165, v64
	v_add_f32_e32 v64, v168, v64
	v_add_f32_e32 v64, v164, v64
	v_add_f32_e32 v64, v166, v64
	v_exp_f32_e32 v239, v68
	s_waitcnt lgkmcnt(0)
	v_mfma_f32_32x32x16_bf16 v[80:95], v[202:205], v[140:143], v[80:95]
	ds_read_b128 v[198:201], v180 offset:16384
	ds_read_b128 v[202:205], v180 offset:24576
	v_add_f32_e32 v64, v238, v64
	v_exp_f32_e32 v240, v69
	v_exp_f32_e32 v241, v70
	v_exp_f32_e32 v242, v71
	s_waitcnt lgkmcnt(1)
	v_mfma_f32_32x32x16_bf16 v[96:111], v[198:201], v[132:135], v[96:111]
	ds_read_b128 v[198:201], v181 offset:16384
	ds_read_b128 v[206:209], v181 offset:24576
	ds_read_b128 v[210:213], v182 offset:16384
	ds_read_b128 v[214:217], v182 offset:24576
	ds_read_b128 v[218:221], v183 offset:16384
	ds_read_b128 v[222:225], v183 offset:24576
	v_exp_f32_e32 v243, v76
	v_exp_f32_e32 v244, v77
	v_exp_f32_e32 v245, v78
	v_exp_f32_e32 v79, v79
	s_waitcnt lgkmcnt(6)
	v_mfma_f32_32x32x16_bf16 v[80:95], v[202:205], v[132:135], v[80:95]
	ds_read_b128 v[202:205], v184 offset:16384
	ds_read_b128 v[226:229], v184 offset:24576
	ds_read_b128 v[230:233], v185 offset:16384
	ds_read_b128 v[234:237], v185 offset:24576
	s_waitcnt lgkmcnt(9)
	v_mfma_f32_32x32x16_bf16 v[96:111], v[198:201], v[128:131], v[96:111]
	v_exp_f32_e32 v199, v65
	v_exp_f32_e32 v200, v66
	v_exp_f32_e32 v201, v67
	v_add_f32_e32 v64, v199, v64
	v_add_f32_e32 v64, v200, v64
	v_add_f32_e32 v64, v201, v64
	s_waitcnt lgkmcnt(8)
	v_mfma_f32_32x32x16_bf16 v[80:95], v[206:209], v[128:131], v[80:95]
	v_exp_f32_e32 v206, v72
	v_add_f32_e32 v64, v239, v64
	v_exp_f32_e32 v207, v73
	v_add_f32_e32 v64, v240, v64
	v_exp_f32_e32 v208, v74
	v_add_f32_e32 v64, v241, v64
	v_exp_f32_e32 v209, v75
	s_waitcnt lgkmcnt(7)
	v_mfma_f32_32x32x16_bf16 v[96:111], v[210:213], v[124:127], v[96:111]
	v_add_f32_e32 v64, v242, v64
	v_add_f32_e32 v64, v206, v64
	v_add_f32_e32 v64, v207, v64
	v_add_f32_e32 v64, v208, v64
	v_add_f32_e32 v64, v209, v64
	v_add_f32_e32 v64, v243, v64
	v_add_f32_e32 v64, v244, v64
	s_waitcnt lgkmcnt(6)
	v_mfma_f32_32x32x16_bf16 v[80:95], v[214:217], v[124:127], v[80:95]
	v_add_f32_e32 v64, v245, v64
	v_add_f32_e32 v198, v79, v64
	v_cvt_pk_bf16_f32 v64, v196, v197
	v_cvt_pk_bf16_f32 v65, v193, v195
	v_cvt_pk_bf16_f32 v66, v191, v194
	v_cvt_pk_bf16_f32 v67, v190, v192
	s_waitcnt lgkmcnt(5)
	v_mfma_f32_32x32x16_bf16 v[96:111], v[218:221], v[120:123], v[96:111]
	v_cvt_pk_bf16_f32 v68, v169, v171
	v_cvt_pk_bf16_f32 v69, v167, v170
	v_cvt_pk_bf16_f32 v70, v165, v168
	v_cvt_pk_bf16_f32 v71, v164, v166
	v_cvt_pk_bf16_f32 v72, v238, v199
	v_cvt_pk_bf16_f32 v73, v200, v201
	v_cvt_pk_bf16_f32 v74, v239, v240
	s_waitcnt lgkmcnt(4)
	v_mfma_f32_32x32x16_bf16 v[80:95], v[222:225], v[120:123], v[80:95]
	v_cvt_pk_bf16_f32 v75, v241, v242
	v_cvt_pk_bf16_f32 v76, v206, v207
	v_cvt_pk_bf16_f32 v77, v208, v209
	v_cvt_pk_bf16_f32 v78, v243, v244
	v_cvt_pk_bf16_f32 v79, v245, v79
	s_waitcnt lgkmcnt(3)
	v_mfma_f32_32x32x16_bf16 v[96:111], v[202:205], v[116:119], v[96:111]
	s_add_i32 s33, s40, 0x8000
	s_and_b32 s43, s33, 0xc000
	ds_read_b64_tr_b16 v[190:191], v176
	ds_read_b64_tr_b16 v[192:193], v176 offset:2048
	ds_read_b64_tr_b16 v[194:195], v176 offset:4096
	ds_read_b64_tr_b16 v[196:197], v176 offset:6144
	s_waitcnt lgkmcnt(6)
	v_mfma_f32_32x32x16_bf16 v[80:95], v[226:229], v[116:119], v[80:95]
	ds_read_b64_tr_b16 v[200:201], v176 offset:8192
	ds_read_b64_tr_b16 v[202:203], v176 offset:10240
	ds_read_b64_tr_b16 v[204:205], v176 offset:12288
	ds_read_b64_tr_b16 v[206:207], v176 offset:14336
	s_add_i32 s73, s40, 0x4000
	s_and_b32 s73, s73, 0xc000
	s_add_u32 s98, s38, s22
	s_addc_u32 s99, s39, s23
	s_add_i32 s41, s66, s73
	s_add_u32 s100, s38, s24
	s_addc_u32 s101, s39, s25
	s_mov_b32 m0, s41
	s_add_i32 s73, s67, s73
	global_load_lds_dwordx4 v156, s[98:99]
	s_waitcnt lgkmcnt(9)
; #define SBAR() __builtin_amdgcn_sched_barrier(0)
; #define PUBLISH(n) do { asm volatile("s_waitcnt vmcnt(" #n ")" ::: "memory"); asm volatile("s_waitcnt lgkmcnt(0)" ::: "memory"); __builtin_amdgcn_s_barrier(); SBAR(); } while (0)
; template <int D0> __device__ __forceinline__ void pv_one(f32x16& od, int vb, bf16x8 pa0, bf16x8 pa1, bf16x8 pa2, bf16x8 pa3) {
;   const s16x4 l0 = tr_read<v_rd_off(D0, 0, 0)>(vb), h0 = tr_read<v_rd_off(D0, 0, 1)>(vb), l1 = tr_read<v_rd_off(D0, 1, 0)>(vb), h1 = tr_read<v_rd_off(D0, 1, 1)>(vb);
;   const s16x4 l2 = tr_read<v_rd_off(D0, 2, 0)>(vb), h2 = tr_read<v_rd_off(D0, 2, 1)>(vb), l3 = tr_read<v_rd_off(D0, 3, 0)>(vb), h3 = tr_read<v_rd_off(D0, 3, 1)>(vb);
;   asm volatile("s_waitcnt lgkmcnt(0)" ::: "memory"); SBAR();
;     ...
;   od = __builtin_amdgcn_mfma_f32_32x32x16_bf16(pa0, PK(l0, h0), od, 0, 0, 0);
;   od = __builtin_amdgcn_mfma_f32_32x32x16_bf16(pa1, PK(l1, h1), od, 0, 0, 0);
;   od = __builtin_amdgcn_mfma_f32_32x32x16_bf16(pa2, PK(l2, h2), od, 0, 0, 0);
;   od = __builtin_amdgcn_mfma_f32_32x32x16_bf16(pa3, PK(l3, h3), od, 0, 0, 0);
;     ...
; }
; __device__ __forceinline__ void pv_d0(f32x16* o, int vb, bf16x8 pa0, bf16x8 pa1, bf16x8 pa2, bf16x8 pa3) {
;   pv_one<0>(o[0], vb, pa0, pa1, pa2, pa3); pv_one<1>(o[1], vb, pa0, pa1, pa2, pa3); pv_one<2>(o[2], vb, pa0, pa1, pa2, pa3); pv_one<3>(o[3], vb, pa0, pa1, pa2, pa3);
; }
; template <typename TQ> ...
;     ...
;     DMA_TILE(j + 2, (j + 2) & 3); SBAR();
;     pv_d0(o, vb0 + ((j - 1) & 3) * (int)SHM_V, pa0, pa1, pa2, pa3); partialSM<true>(pB0, pB1, m_reg, mnB, alB);
;     PUBLISH(4);
;     SBAR(); qkt(pA0, pA1, (const bf16*)(K_lds + ((j + 1) & 3) * (int)SHM_K), qr, r32, hi);
	v_mfma_f32_32x32x16_bf16 v[96:111], v[230:233], v[112:115], v[96:111]
	s_add_i32 m0, s41, 0x2000
	s_nop 0
	global_load_lds_dwordx4 v158, s[98:99]
	s_mov_b32 m0, s73
	s_nop 0
	global_load_lds_dwordx4 v162, s[100:101]
	s_waitcnt lgkmcnt(8)
	v_mfma_f32_32x32x16_bf16 v[80:95], v[234:237], v[112:115], v[80:95]
	s_add_i32 m0, s73, 0x2000
	s_nop 0
	global_load_lds_dwordx4 v160, s[100:101]
	s_nop 0
	s_waitcnt lgkmcnt(6)
	v_mfma_f32_32x32x16_bf16 v[48:63], v[64:67], v[190:193], v[48:63]
	v_exp_f32_e32 v232, v96
	ds_read_b64_tr_b16 v[190:191], v176 offset:512
	ds_read_b64_tr_b16 v[192:193], v176 offset:2560
	s_waitcnt lgkmcnt(6)
	v_mfma_f32_32x32x16_bf16 v[48:63], v[68:71], v[194:197], v[48:63]
	v_exp_f32_e32 v233, v97
	ds_read_b64_tr_b16 v[194:195], v176 offset:4608
	ds_read_b64_tr_b16 v[196:197], v176 offset:6656
	s_waitcnt lgkmcnt(6)
	v_mfma_f32_32x32x16_bf16 v[48:63], v[72:75], v[200:203], v[48:63]
	v_exp_f32_e32 v234, v98
	ds_read_b64_tr_b16 v[200:201], v176 offset:8704
	ds_read_b64_tr_b16 v[202:203], v176 offset:10752
	ds_read_b64_tr_b16 v[208:209], v176 offset:12800
	ds_read_b64_tr_b16 v[210:211], v176 offset:14848
	s_waitcnt lgkmcnt(8)
	v_mfma_f32_32x32x16_bf16 v[48:63], v[76:79], v[204:207], v[48:63]
	v_exp_f32_e32 v235, v99
	s_waitcnt lgkmcnt(6)
	v_mfma_f32_32x32x16_bf16 v[32:47], v[64:67], v[190:193], v[32:47]
	v_exp_f32_e32 v236, v100
	ds_read_b64_tr_b16 v[190:191], v176 offset:1024
	ds_read_b64_tr_b16 v[192:193], v176 offset:3072
	s_waitcnt lgkmcnt(6)
	v_mfma_f32_32x32x16_bf16 v[32:47], v[68:71], v[194:197], v[32:47]
	v_exp_f32_e32 v237, v101
	ds_read_b64_tr_b16 v[194:195], v176 offset:5120
	ds_read_b64_tr_b16 v[196:197], v176 offset:7168
	s_waitcnt lgkmcnt(6)
	v_mfma_f32_32x32x16_bf16 v[32:47], v[72:75], v[200:203], v[32:47]
	v_exp_f32_e32 v238, v102
	ds_read_b64_tr_b16 v[200:201], v176 offset:9216
	ds_read_b64_tr_b16 v[202:203], v176 offset:11264
	ds_read_b64_tr_b16 v[204:205], v176 offset:13312
	ds_read_b64_tr_b16 v[206:207], v176 offset:15360
	s_waitcnt lgkmcnt(8)
	v_mfma_f32_32x32x16_bf16 v[32:47], v[76:79], v[208:211], v[32:47]
	v_exp_f32_e32 v239, v103
	v_exp_f32_e32 v240, v104
	s_waitcnt lgkmcnt(6)
	v_mfma_f32_32x32x16_bf16 v[16:31], v[64:67], v[190:193], v[16:31]
	v_exp_f32_e32 v241, v105
	ds_read_b64_tr_b16 v[190:191], v176 offset:1536
	ds_read_b64_tr_b16 v[192:193], v176 offset:3584
	s_waitcnt lgkmcnt(6)
	v_mfma_f32_32x32x16_bf16 v[16:31], v[68:71], v[194:197], v[16:31]
	v_exp_f32_e32 v242, v106
	ds_read_b64_tr_b16 v[194:195], v176 offset:5632
	ds_read_b64_tr_b16 v[196:197], v176 offset:7680
	s_waitcnt lgkmcnt(6)
	v_mfma_f32_32x32x16_bf16 v[16:31], v[72:75], v[200:203], v[16:31]
	v_exp_f32_e32 v243, v107
	ds_read_b64_tr_b16 v[200:201], v176 offset:9728
	ds_read_b64_tr_b16 v[202:203], v176 offset:11776
	ds_read_b64_tr_b16 v[208:209], v176 offset:13824
	ds_read_b64_tr_b16 v[210:211], v176 offset:15872
	s_waitcnt lgkmcnt(8)
	v_mfma_f32_32x32x16_bf16 v[16:31], v[76:79], v[204:207], v[16:31]
	v_exp_f32_e32 v244, v108
	s_waitcnt lgkmcnt(6)
	v_mfma_f32_32x32x16_bf16 v[0:15], v[64:67], v[190:193], v[0:15]
	v_exp_f32_e32 v245, v109
	s_waitcnt lgkmcnt(4)
	v_mfma_f32_32x32x16_bf16 v[0:15], v[68:71], v[194:197], v[0:15]
	v_exp_f32_e32 v246, v110
	s_waitcnt lgkmcnt(2)
	v_mfma_f32_32x32x16_bf16 v[0:15], v[72:75], v[200:203], v[0:15]
	v_exp_f32_e32 v247, v111
	s_waitcnt vmcnt(4)
	s_waitcnt lgkmcnt(0)
	s_barrier
	v_mfma_f32_32x32x16_bf16 v[0:15], v[76:79], v[208:211], v[0:15]
	s_and_b32 s40, s40, 0xc000
	s_add_i32 s40, s56, s40
	ds_read_b128 v[64:67], v178 offset:32768
	ds_read_b128 v[68:71], v178 offset:40960
	ds_read_b128 v[190:193], v179 offset:32768
	ds_read_b128 v[194:197], v179 offset:40960
	s_waitcnt lgkmcnt(3)
	v_mfma_f32_32x32x16_bf16 v[96:111], v[64:67], v[136:139], 0
	v_exp_f32_e32 v80, v80
	v_exp_f32_e32 v81, v81
	v_exp_f32_e32 v82, v82
	v_exp_f32_e32 v83, v83
	v_exp_f32_e32 v87, v87
	v_exp_f32_e32 v248, v93
	v_exp_f32_e32 v249, v94
	s_waitcnt lgkmcnt(2)
	v_mfma_f32_32x32x16_bf16 v[64:79], v[68:71], v[136:139], 0
	s_waitcnt lgkmcnt(1)
	v_mfma_f32_32x32x16_bf16 v[96:111], v[190:193], v[140:143], v[96:111]
	s_waitcnt lgkmcnt(0)
	v_mfma_f32_32x32x16_bf16 v[64:79], v[194:197], v[140:143], v[64:79]
	ds_read_b128 v[190:193], v180 offset:32768
	ds_read_b128 v[194:197], v180 offset:40960
	s_waitcnt lgkmcnt(1)
	v_mfma_f32_32x32x16_bf16 v[96:111], v[190:193], v[132:135], v[96:111]
	ds_read_b128 v[190:193], v181 offset:32768
	ds_read_b128 v[200:203], v181 offset:40960
	ds_read_b128 v[204:207], v182 offset:32768
	ds_read_b128 v[208:211], v182 offset:40960
	ds_read_b128 v[212:215], v183 offset:32768
	ds_read_b128 v[216:219], v183 offset:40960
	s_waitcnt lgkmcnt(6)
	v_mfma_f32_32x32x16_bf16 v[64:79], v[194:197], v[132:135], v[64:79]
	ds_read_b128 v[194:197], v184 offset:32768
	ds_read_b128 v[220:223], v184 offset:40960
	ds_read_b128 v[224:227], v185 offset:32768
	ds_read_b128 v[228:231], v185 offset:40960
	s_waitcnt lgkmcnt(9)
	v_mfma_f32_32x32x16_bf16 v[96:111], v[190:193], v[128:131], v[96:111]
	s_cmp_ge_u32 s72, s37
	s_cselect_b64 s[40:41], -1, 0
	s_and_b64 vcc, exec, s[40:41]
	s_cbranch_vccnz .LBB0_1367
	s_add_i32 s73, s66, s43
	s_add_u32 s98, s38, s26
	s_addc_u32 s99, s39, s27
	s_mov_b32 m0, s73
	s_add_i32 s43, s67, s43
	global_load_lds_dwordx4 v156, s[98:99]
	s_add_u32 s100, s38, s28
	s_addc_u32 s101, s39, s29
	s_add_i32 m0, s73, 0x2000
	s_nop 0
	global_load_lds_dwordx4 v158, s[98:99]
	s_mov_b32 m0, s43
	s_nop 0
	global_load_lds_dwordx4 v162, s[100:101]
	s_add_i32 m0, s43, 0x2000
	s_nop 0
	global_load_lds_dwordx4 v160, s[100:101]

; #define SBAR() __builtin_amdgcn_sched_barrier(0)
; #define PK4(P, BASE, OUT) do { u32x4 w = {cvtpk(P[BASE + 0], P[BASE + 1]), cvtpk(P[BASE + 2], P[BASE + 3]), cvtpk(P[BASE + 4], P[BASE + 5]), cvtpk(P[BASE + 6], P[BASE + 7])}; \
;     OUT = *reinterpret_cast<bf16x8*>(&w); } while (0)
; __device__ __forceinline__ void finishSM(f32x16& p0, f32x16& p1, float alpha, float& l_reg, bf16x8& pa0, bf16x8& pa1, bf16x8& pa2, bf16x8& pa3) {
;   for (int r = 0; r < 16; ++r) p1[r] = __builtin_amdgcn_exp2f(p1[r]);
;   float ps = 0; for (int r = 0; r < 16; ++r) ps += p0[r]; for (int r = 0; r < 16; ++r) ps += p1[r];
;   asm volatile("" : "+v"(ps));
;   l_reg = l_reg * alpha + ps;
;     ...
;   PK4(p0, 0, pa0); PK4(p0, 8, pa1); PK4(p1, 0, pa2); PK4(p1, 8, pa3);
;     ...
; }
; __device__ __forceinline__ void qkt(f32x16& p0, f32x16& p1, const bf16* Ks, const bf16x8* qr, int r32, int hi) {
;   p0 = f32x16{}; p1 = f32x16{};
;   for (int d0 = 0; d0 < 8; ++d0) { int cb = (d0 * 16 + hi * 8) * 2;
;     bf16x8 b0 = *reinterpret_cast<const bf16x8*>((const char*)Ks + KSWZ(r32, cb));
;     bf16x8 b1 = *reinterpret_cast<const bf16x8*>((const char*)Ks + KSWZ(32 + r32, cb));
;     p0 = __builtin_amdgcn_mfma_f32_32x32x16_bf16(b0, qr[d0], p0, 0, 0, 0);
;     p1 = __builtin_amdgcn_mfma_f32_32x32x16_bf16(b1, qr[d0], p1, 0, 0, 0); }
; }
; template <typename TQ> ...
;     ...
;     SBAR(); qkt(pA0, pA1, (const bf16*)(K_lds + ((j + 1) & 3) * (int)SHM_K), qr, r32, hi);
;     finishSM(pB0, pB1, alB, l_reg, pa0, pa1, pa2, pa3); SBAR();
;     if (j + 3 < NT) { DMA_TILE(j + 3, (j + 3) & 3); } SBAR();
;     pv_d0(o, vb0 + (j & 3) * (int)SHM_V, pa0, pa1, pa2, pa3); partialSM<true>(pA0, pA1, m_reg, mnA, alA);
.Lat1365_b:
.Lat1365_b_in:
	s_mov_b32 s40, s33
	s_addk_i32 s33, 0xc000
	s_and_b32 s42, s33, 0xc000
	s_add_i32 s33, s56, s42
	ds_read_b128 v[80:83], v178 offset:49152
	ds_read_b128 v[84:87], v178 offset:57344
	ds_read_b128 v[198:201], v179 offset:49152
	ds_read_b128 v[202:205], v179 offset:57344
	v_exp_f32_e32 v196, v96
	v_exp_f32_e32 v197, v97
	v_exp_f32_e32 v193, v98
	v_exp_f32_e32 v195, v99
	v_exp_f32_e32 v191, v100
	v_exp_f32_e32 v194, v101
	v_exp_f32_e32 v190, v102
	v_exp_f32_e32 v192, v103
	v_exp_f32_e32 v169, v104
	v_exp_f32_e32 v171, v105
	v_exp_f32_e32 v167, v106
	v_exp_f32_e32 v170, v107
	v_exp_f32_e32 v165, v108
	v_exp_f32_e32 v168, v109
	v_exp_f32_e32 v164, v110
	v_exp_f32_e32 v166, v111
	s_waitcnt lgkmcnt(3)
	v_mfma_f32_32x32x16_bf16 v[96:111], v[80:83], v[136:139], 0
	v_exp_f32_e32 v238, v64
	v_add_f32_e32 v64, v197, v196
	v_add_f32_e32 v64, v193, v64
	v_add_f32_e32 v64, v195, v64
	s_waitcnt lgkmcnt(2)
	v_mfma_f32_32x32x16_bf16 v[80:95], v[84:87], v[136:139], 0
	v_add_f32_e32 v64, v191, v64
	v_add_f32_e32 v64, v194, v64
	v_add_f32_e32 v64, v190, v64
	v_add_f32_e32 v64, v192, v64
	v_add_f32_e32 v64, v169, v64
	v_add_f32_e32 v64, v171, v64
	s_waitcnt lgkmcnt(1)
	v_mfma_f32_32x32x16_bf16 v[96:111], v[198:201], v[140:143], v[96:111]
	v_add_f32_e32 v64, v167, v64
	v_add_f32_e32 v64, v170, v64
	v_add_f32_e32 v64, v165, v64
	v_add_f32_e32 v64, v168, v64
	v_add_f32_e32 v64, v164, v64
	v_add_f32_e32 v64, v166, v64
	v_exp_f32_e32 v239, v68
	s_waitcnt lgkmcnt(0)
	v_mfma_f32_32x32x16_bf16 v[80:95], v[202:205], v[140:143], v[80:95]
	ds_read_b128 v[198:201], v180 offset:49152
	ds_read_b128 v[202:205], v180 offset:57344
	v_add_f32_e32 v64, v238, v64
	v_exp_f32_e32 v240, v69
	v_exp_f32_e32 v241, v70
	v_exp_f32_e32 v242, v71
	s_waitcnt lgkmcnt(1)
	v_mfma_f32_32x32x16_bf16 v[96:111], v[198:201], v[132:135], v[96:111]
	ds_read_b128 v[198:201], v181 offset:49152
	ds_read_b128 v[206:209], v181 offset:57344
	ds_read_b128 v[210:213], v182 offset:49152
	ds_read_b128 v[214:217], v182 offset:57344
	ds_read_b128 v[218:221], v183 offset:49152
	ds_read_b128 v[222:225], v183 offset:57344
	v_exp_f32_e32 v243, v76
	v_exp_f32_e32 v244, v77
	v_exp_f32_e32 v245, v78
	v_exp_f32_e32 v79, v79
	s_waitcnt lgkmcnt(6)
	v_mfma_f32_32x32x16_bf16 v[80:95], v[202:205], v[132:135], v[80:95]
	ds_read_b128 v[202:205], v184 offset:49152
	ds_read_b128 v[226:229], v184 offset:57344
	ds_read_b128 v[230:233], v185 offset:49152
	ds_read_b128 v[234:237], v185 offset:57344
	s_waitcnt lgkmcnt(9)
	v_mfma_f32_32x32x16_bf16 v[96:111], v[198:201], v[128:131], v[96:111]
	v_exp_f32_e32 v199, v65
	v_exp_f32_e32 v200, v66
	v_exp_f32_e32 v201, v67
	v_add_f32_e32 v64, v199, v64
	v_add_f32_e32 v64, v200, v64
	v_add_f32_e32 v64, v201, v64
	s_waitcnt lgkmcnt(8)
	v_mfma_f32_32x32x16_bf16 v[80:95], v[206:209], v[128:131], v[80:95]
	v_exp_f32_e32 v206, v72
	v_add_f32_e32 v64, v239, v64
	v_exp_f32_e32 v207, v73
	v_add_f32_e32 v64, v240, v64
	v_exp_f32_e32 v208, v74
	v_add_f32_e32 v64, v241, v64
	v_exp_f32_e32 v209, v75
	s_waitcnt lgkmcnt(7)
	v_mfma_f32_32x32x16_bf16 v[96:111], v[210:213], v[124:127], v[96:111]
	v_add_f32_e32 v64, v242, v64
	v_add_f32_e32 v64, v206, v64
	v_add_f32_e32 v64, v207, v64
	v_add_f32_e32 v64, v208, v64
	v_add_f32_e32 v64, v209, v64
	v_add_f32_e32 v64, v243, v64
	v_add_f32_e32 v64, v244, v64
	s_waitcnt lgkmcnt(6)
	v_mfma_f32_32x32x16_bf16 v[80:95], v[214:217], v[124:127], v[80:95]
	v_add_f32_e32 v64, v245, v64
	v_add_f32_e32 v198, v79, v64
	v_cvt_pk_bf16_f32 v64, v196, v197
	v_cvt_pk_bf16_f32 v65, v193, v195
	v_cvt_pk_bf16_f32 v66, v191, v194
	v_cvt_pk_bf16_f32 v67, v190, v192
	s_waitcnt lgkmcnt(5)
	v_mfma_f32_32x32x16_bf16 v[96:111], v[218:221], v[120:123], v[96:111]
	v_cvt_pk_bf16_f32 v68, v169, v171
	v_cvt_pk_bf16_f32 v69, v167, v170
	v_cvt_pk_bf16_f32 v70, v165, v168
	v_cvt_pk_bf16_f32 v71, v164, v166
	v_cvt_pk_bf16_f32 v72, v238, v199
	v_cvt_pk_bf16_f32 v73, v200, v201
	v_cvt_pk_bf16_f32 v74, v239, v240
	s_waitcnt lgkmcnt(4)
	v_mfma_f32_32x32x16_bf16 v[80:95], v[222:225], v[120:123], v[80:95]
	v_cvt_pk_bf16_f32 v75, v241, v242
	v_cvt_pk_bf16_f32 v76, v206, v207
	v_cvt_pk_bf16_f32 v77, v208, v209
	v_cvt_pk_bf16_f32 v78, v243, v244
	v_cvt_pk_bf16_f32 v79, v245, v79
	s_waitcnt lgkmcnt(3)
	v_mfma_f32_32x32x16_bf16 v[96:111], v[202:205], v[116:119], v[96:111]
	s_add_i32 s33, s40, 0x8000
	s_and_b32 s43, s33, 0xc000
	ds_read_b64_tr_b16 v[190:191], v176 offset:32768
	ds_read_b64_tr_b16 v[192:193], v176 offset:34816
	ds_read_b64_tr_b16 v[194:195], v176 offset:36864
	ds_read_b64_tr_b16 v[196:197], v176 offset:38912
	s_waitcnt lgkmcnt(6)
	v_mfma_f32_32x32x16_bf16 v[80:95], v[226:229], v[116:119], v[80:95]
	ds_read_b64_tr_b16 v[200:201], v176 offset:40960
	ds_read_b64_tr_b16 v[202:203], v176 offset:43008
	ds_read_b64_tr_b16 v[204:205], v176 offset:45056
	ds_read_b64_tr_b16 v[206:207], v176 offset:47104
	s_add_i32 s73, s40, 0x4000
	s_and_b32 s73, s73, 0xc000
	s_add_u32 s98, s38, s22
	s_addc_u32 s99, s39, s23
	s_add_i32 s41, s66, s73
	s_add_u32 s100, s38, s24
	s_addc_u32 s101, s39, s25
	s_mov_b32 m0, s41
	s_add_i32 s73, s67, s73
	global_load_lds_dwordx4 v156, s[98:99]
	s_waitcnt lgkmcnt(9)
; #define SBAR() __builtin_amdgcn_sched_barrier(0)
; #define PUBLISH(n) do { asm volatile("s_waitcnt vmcnt(" #n ")" ::: "memory"); asm volatile("s_waitcnt lgkmcnt(0)" ::: "memory"); __builtin_amdgcn_s_barrier(); SBAR(); } while (0)
; template <int D0> __device__ __forceinline__ void pv_one(f32x16& od, int vb, bf16x8 pa0, bf16x8 pa1, bf16x8 pa2, bf16x8 pa3) {
;   const s16x4 l0 = tr_read<v_rd_off(D0, 0, 0)>(vb), h0 = tr_read<v_rd_off(D0, 0, 1)>(vb), l1 = tr_read<v_rd_off(D0, 1, 0)>(vb), h1 = tr_read<v_rd_off(D0, 1, 1)>(vb);
;   const s16x4 l2 = tr_read<v_rd_off(D0, 2, 0)>(vb), h2 = tr_read<v_rd_off(D0, 2, 1)>(vb), l3 = tr_read<v_rd_off(D0, 3, 0)>(vb), h3 = tr_read<v_rd_off(D0, 3, 1)>(vb);
;   asm volatile("s_waitcnt lgkmcnt(0)" ::: "memory"); SBAR();
;     ...
;   od = __builtin_amdgcn_mfma_f32_32x32x16_bf16(pa0, PK(l0, h0), od, 0, 0, 0);
;   od = __builtin_amdgcn_mfma_f32_32x32x16_bf16(pa1, PK(l1, h1), od, 0, 0, 0);
;   od = __builtin_amdgcn_mfma_f32_32x32x16_bf16(pa2, PK(l2, h2), od, 0, 0, 0);
;   od = __builtin_amdgcn_mfma_f32_32x32x16_bf16(pa3, PK(l3, h3), od, 0, 0, 0);
;     ...
; }
; __device__ __forceinline__ void pv_d0(f32x16* o, int vb, bf16x8 pa0, bf16x8 pa1, bf16x8 pa2, bf16x8 pa3) {
;   pv_one<0>(o[0], vb, pa0, pa1, pa2, pa3); pv_one<1>(o[1], vb, pa0, pa1, pa2, pa3); pv_one<2>(o[2], vb, pa0, pa1, pa2, pa3); pv_one<3>(o[3], vb, pa0, pa1, pa2, pa3);
; }
; template <typename TQ> ...
;     ...
;   for (int j = 1; j + 1 < NT; j += 2) {
;     SBAR(); qkt(pB0, pB1, (const bf16*)(K_lds + (j & 3) * (int)SHM_K), qr, r32, hi);
;     finishSM(pA0, pA1, alA, l_reg, pa0, pa1, pa2, pa3); SBAR();
;     DMA_TILE(j + 2, (j + 2) & 3); SBAR();
;     pv_d0(o, vb0 + ((j - 1) & 3) * (int)SHM_V, pa0, pa1, pa2, pa3); partialSM<true>(pB0, pB1, m_reg, mnB, alB);
;     PUBLISH(4);
;     SBAR(); qkt(pA0, pA1, (const bf16*)(K_lds + ((j + 1) & 3) * (int)SHM_K), qr, r32, hi);
;     finishSM(pB0, pB1, alB, l_reg, pa0, pa1, pa2, pa3); SBAR();
;     if (j + 3 < NT) { DMA_TILE(j + 3, (j + 3) & 3); } SBAR();
;     pv_d0(o, vb0 + (j & 3) * (int)SHM_V, pa0, pa1, pa2, pa3); partialSM<true>(pA0, pA1, m_reg, mnA, alA);
;     if (j + 3 < NT) { PUBLISH(4); } else { PUBLISH(0); }
;   }
	v_mfma_f32_32x32x16_bf16 v[96:111], v[230:233], v[112:115], v[96:111]
	s_add_i32 m0, s41, 0x2000
	s_nop 0
	global_load_lds_dwordx4 v158, s[98:99]
	s_mov_b32 m0, s73
	s_nop 0
	global_load_lds_dwordx4 v162, s[100:101]
	s_waitcnt lgkmcnt(8)
	v_mfma_f32_32x32x16_bf16 v[80:95], v[234:237], v[112:115], v[80:95]
	s_add_i32 m0, s73, 0x2000
	s_nop 0
	global_load_lds_dwordx4 v160, s[100:101]
	s_nop 0
	s_waitcnt lgkmcnt(6)
	v_mfma_f32_32x32x16_bf16 v[48:63], v[64:67], v[190:193], v[48:63]
	v_exp_f32_e32 v232, v96
	ds_read_b64_tr_b16 v[190:191], v176 offset:33280
	ds_read_b64_tr_b16 v[192:193], v176 offset:35328
	s_waitcnt lgkmcnt(6)
	v_mfma_f32_32x32x16_bf16 v[48:63], v[68:71], v[194:197], v[48:63]
	v_exp_f32_e32 v233, v97
	ds_read_b64_tr_b16 v[194:195], v176 offset:37376
	ds_read_b64_tr_b16 v[196:197], v176 offset:39424
	s_waitcnt lgkmcnt(6)
	v_mfma_f32_32x32x16_bf16 v[48:63], v[72:75], v[200:203], v[48:63]
	v_exp_f32_e32 v234, v98
	ds_read_b64_tr_b16 v[200:201], v176 offset:41472
	ds_read_b64_tr_b16 v[202:203], v176 offset:43520
	ds_read_b64_tr_b16 v[208:209], v176 offset:45568
	ds_read_b64_tr_b16 v[210:211], v176 offset:47616
	s_waitcnt lgkmcnt(8)
	v_mfma_f32_32x32x16_bf16 v[48:63], v[76:79], v[204:207], v[48:63]
	v_exp_f32_e32 v235, v99
	s_waitcnt lgkmcnt(6)
	v_mfma_f32_32x32x16_bf16 v[32:47], v[64:67], v[190:193], v[32:47]
	v_exp_f32_e32 v236, v100
	ds_read_b64_tr_b16 v[190:191], v176 offset:33792
	ds_read_b64_tr_b16 v[192:193], v176 offset:35840
	s_waitcnt lgkmcnt(6)
	v_mfma_f32_32x32x16_bf16 v[32:47], v[68:71], v[194:197], v[32:47]
	v_exp_f32_e32 v237, v101
	ds_read_b64_tr_b16 v[194:195], v176 offset:37888
	ds_read_b64_tr_b16 v[196:197], v176 offset:39936
	s_waitcnt lgkmcnt(6)
	v_mfma_f32_32x32x16_bf16 v[32:47], v[72:75], v[200:203], v[32:47]
	v_exp_f32_e32 v238, v102
	ds_read_b64_tr_b16 v[200:201], v176 offset:41984
	ds_read_b64_tr_b16 v[202:203], v176 offset:44032
	ds_read_b64_tr_b16 v[204:205], v176 offset:46080
	ds_read_b64_tr_b16 v[206:207], v176 offset:48128
	s_waitcnt lgkmcnt(8)
	v_mfma_f32_32x32x16_bf16 v[32:47], v[76:79], v[208:211], v[32:47]
	v_exp_f32_e32 v239, v103
	v_exp_f32_e32 v240, v104
	s_waitcnt lgkmcnt(6)
	v_mfma_f32_32x32x16_bf16 v[16:31], v[64:67], v[190:193], v[16:31]
	v_exp_f32_e32 v241, v105
	ds_read_b64_tr_b16 v[190:191], v176 offset:34304
	ds_read_b64_tr_b16 v[192:193], v176 offset:36352
	s_waitcnt lgkmcnt(6)
	v_mfma_f32_32x32x16_bf16 v[16:31], v[68:71], v[194:197], v[16:31]
	v_exp_f32_e32 v242, v106
	ds_read_b64_tr_b16 v[194:195], v176 offset:38400
	ds_read_b64_tr_b16 v[196:197], v176 offset:40448
	s_waitcnt lgkmcnt(6)
	v_mfma_f32_32x32x16_bf16 v[16:31], v[72:75], v[200:203], v[16:31]
	v_exp_f32_e32 v243, v107
	ds_read_b64_tr_b16 v[200:201], v176 offset:42496
	ds_read_b64_tr_b16 v[202:203], v176 offset:44544
	ds_read_b64_tr_b16 v[208:209], v176 offset:46592
	ds_read_b64_tr_b16 v[210:211], v176 offset:48640
	s_waitcnt lgkmcnt(8)
	v_mfma_f32_32x32x16_bf16 v[16:31], v[76:79], v[204:207], v[16:31]
	v_exp_f32_e32 v244, v108
	s_waitcnt lgkmcnt(6)
	v_mfma_f32_32x32x16_bf16 v[0:15], v[64:67], v[190:193], v[0:15]
	v_exp_f32_e32 v245, v109
	s_waitcnt lgkmcnt(4)
	v_mfma_f32_32x32x16_bf16 v[0:15], v[68:71], v[194:197], v[0:15]
	v_exp_f32_e32 v246, v110
	s_waitcnt lgkmcnt(2)
	v_mfma_f32_32x32x16_bf16 v[0:15], v[72:75], v[200:203], v[0:15]
	v_exp_f32_e32 v247, v111
	s_waitcnt vmcnt(4)
	s_waitcnt lgkmcnt(0)
	s_barrier
	v_mfma_f32_32x32x16_bf16 v[0:15], v[76:79], v[208:211], v[0:15]
	s_and_b32 s40, s40, 0xc000
	s_add_i32 s40, s56, s40
	ds_read_b128 v[64:67], v178
	ds_read_b128 v[68:71], v178 offset:8192
	ds_read_b128 v[190:193], v179
	ds_read_b128 v[194:197], v179 offset:8192
	s_waitcnt lgkmcnt(3)
	v_mfma_f32_32x32x16_bf16 v[96:111], v[64:67], v[136:139], 0
	v_exp_f32_e32 v80, v80
	v_exp_f32_e32 v81, v81
	v_exp_f32_e32 v82, v82
	v_exp_f32_e32 v83, v83
	v_exp_f32_e32 v87, v87
	v_exp_f32_e32 v248, v93
	v_exp_f32_e32 v249, v94
	s_waitcnt lgkmcnt(2)
	v_mfma_f32_32x32x16_bf16 v[64:79], v[68:71], v[136:139], 0
	s_waitcnt lgkmcnt(1)
	v_mfma_f32_32x32x16_bf16 v[96:111], v[190:193], v[140:143], v[96:111]
	s_waitcnt lgkmcnt(0)
	v_mfma_f32_32x32x16_bf16 v[64:79], v[194:197], v[140:143], v[64:79]
	ds_read_b128 v[190:193], v180
	ds_read_b128 v[194:197], v180 offset:8192
	s_waitcnt lgkmcnt(1)
	v_mfma_f32_32x32x16_bf16 v[96:111], v[190:193], v[132:135], v[96:111]
	ds_read_b128 v[190:193], v181
	ds_read_b128 v[200:203], v181 offset:8192
	ds_read_b128 v[204:207], v182
	ds_read_b128 v[208:211], v182 offset:8192
	ds_read_b128 v[212:215], v183
	ds_read_b128 v[216:219], v183 offset:8192
	s_waitcnt lgkmcnt(6)
	v_mfma_f32_32x32x16_bf16 v[64:79], v[194:197], v[132:135], v[64:79]
	ds_read_b128 v[194:197], v184
	ds_read_b128 v[220:223], v184 offset:8192
	ds_read_b128 v[224:227], v185
	ds_read_b128 v[228:231], v185 offset:8192
	s_waitcnt lgkmcnt(9)
	v_mfma_f32_32x32x16_bf16 v[96:111], v[190:193], v[128:131], v[96:111]
	s_cmp_ge_u32 s72, s37
	s_cselect_b64 s[40:41], -1, 0
	s_and_b64 vcc, exec, s[40:41]
	s_cbranch_vccnz .Lat1367_b

; #define SBAR() __builtin_amdgcn_sched_barrier(0)
; template <typename TQ> ...
;     ...
;     if (j + 3 < NT) { DMA_TILE(j + 3, (j + 3) & 3); } SBAR();
	s_add_i32 s73, s66, s43
	s_add_u32 s98, s38, s26
	s_addc_u32 s99, s39, s27
	s_mov_b32 m0, s73
	s_add_i32 s43, s67, s43
	global_load_lds_dwordx4 v156, s[98:99]
	s_add_u32 s100, s38, s28
	s_addc_u32 s101, s39, s29
	s_add_i32 m0, s73, 0x2000
	s_nop 0
	global_load_lds_dwordx4 v158, s[98:99]
	s_mov_b32 m0, s43
	s_nop 0
	global_load_lds_dwordx4 v162, s[100:101]
	s_add_i32 m0, s43, 0x2000
	s_nop 0
	global_load_lds_dwordx4 v160, s[100:101]

; #define SBAR() __builtin_amdgcn_sched_barrier(0)
; #define PUBLISH(n) do { asm volatile("s_waitcnt vmcnt(" #n ")" ::: "memory"); asm volatile("s_waitcnt lgkmcnt(0)" ::: "memory"); __builtin_amdgcn_s_barrier(); SBAR(); } while (0)
; template <typename TQ> ...
;     ...
;   qkt(pA0, pA1, (const bf16*)K_lds, qr, r32, hi); partialSM<true>(pA0, pA1, m_reg, mnA, alA);
;   DMA_TILE(2, 2);
;   PUBLISH(4);
;   for (int j = 1; j + 1 < NT; j += 2) {
;     SBAR(); qkt(pB0, pB1, (const bf16*)(K_lds + (j & 3) * (int)SHM_K), qr, r32, hi);
.LBB0_1365:
	s_mov_b32 s40, s33
	s_addk_i32 s33, 0xc000
	s_and_b32 s42, s33, 0xc000
	s_add_i32 s33, s56, s42
	ds_read_b128 v[80:83], v178 offset:16384
	ds_read_b128 v[84:87], v178 offset:24576
	ds_read_b128 v[198:201], v179 offset:16384
	ds_read_b128 v[202:205], v179 offset:24576
	s_branch .Lat1365_a_go
